# FFN-up heads: sample-row fix-up published with write-through stores, 256 per-workgroup release fences (buffer_wbl2) dropped
# speedup vs baseline: 1.0187x; 1.0187x over previous
; template <bool FINAL>
; __device__ __forceinline__ void sample_fixup(const Params& p, int S, float* ss_s, const float* gf) {
;     ...
;         unsigned long long* o8 = (unsigned long long*)(XB + (size_t)r * D) + lane;
; #pragma unroll
;         for (int j = 0; j < 4; ++j) { const unsigned long long w = o8[64 * j]; const unsigned lo = (unsigned)w, hi = (unsigned)(w >> 32);
;             v[j] = (f32x4){__uint_as_float(lo << 16), __uint_as_float(lo & 0xffff0000u), __uint_as_float(hi << 16), __uint_as_float(hi & 0xffff0000u)}; }
;         for (int sp = 0; sp < S; ++sp) {
;             const unsigned long long* pr = (const unsigned long long*)((const bf16*)part + ((size_t)sp * MS + r) * D) + lane;
; #pragma unroll
;             for (int j = 0; j < 4; ++j) { const unsigned long long w = pr[64 * j]; const unsigned lo = (unsigned)w, hi = (unsigned)(w >> 32);
;                 v[j] += (f32x4){__uint_as_float(lo << 16), __uint_as_float(lo & 0xffff0000u), __uint_as_float(hi << 16), __uint_as_float(hi & 0xffff0000u)}; }
;         }
.LBB0_468:
	s_waitcnt lgkmcnt(0)
	v_lshl_add_u64 v[14:15], s[72:73], 0, v[4:5]
	v_add_co_u32_e32 v16, vcc, s6, v14
	v_add_co_u32_e64 v24, s[2:3], s7, v14
	s_nop 0
	v_addc_co_u32_e32 v17, vcc, 0, v15, vcc
	global_load_dwordx2 v[18:19], v[16:17], off
	global_load_dwordx2 v[20:21], v[16:17], off offset:512
	global_load_dwordx2 v[22:23], v[16:17], off offset:1024
	v_add_co_u32_e32 v6, vcc, 0x4e00000, v14
	global_load_dwordx2 v[16:17], v[16:17], off offset:1536
	v_addc_co_u32_e64 v25, s[2:3], 0, v15, s[2:3]
	v_addc_co_u32_e32 v7, vcc, 0, v15, vcc
	global_load_dwordx2 v[26:27], v[24:25], off
	global_load_dwordx2 v[28:29], v[6:7], off
	global_load_dwordx2 v[30:31], v[6:7], off offset:512
	global_load_dwordx2 v[32:33], v[6:7], off offset:1024
	global_load_dwordx2 v[34:35], v[6:7], off offset:1536
	global_load_dwordx2 v[36:37], v[24:25], off offset:512
	global_load_dwordx2 v[38:39], v[24:25], off offset:1024
	s_nop 0
	global_load_dwordx2 v[24:25], v[24:25], off offset:1536
	v_add_co_u32_e32 v40, vcc, s8, v14
	s_waitcnt vmcnt(11)
	v_lshlrev_b32_e32 v54, 16, v18
	v_addc_co_u32_e32 v41, vcc, 0, v15, vcc
	global_load_dwordx2 v[42:43], v[40:41], off
	global_load_dwordx2 v[44:45], v[40:41], off offset:512
	v_add_co_u32_e32 v14, vcc, s9, v14
	v_and_b32_e32 v55, 0xffff0000, v18
	s_nop 0
	v_addc_co_u32_e32 v15, vcc, 0, v15, vcc
	global_load_dwordx2 v[46:47], v[40:41], off offset:1024
	s_nop 0
	global_load_dwordx2 v[40:41], v[40:41], off offset:1536
	s_nop 0
	global_load_dwordx2 v[48:49], v[14:15], off
	global_load_dwordx2 v[50:51], v[14:15], off offset:512
	global_load_dwordx2 v[52:53], v[14:15], off offset:1024
	s_nop 0
	global_load_dwordx2 v[14:15], v[14:15], off offset:1536
	v_lshlrev_b32_e32 v18, 16, v19
	v_and_b32_e32 v19, 0xffff0000, v19
	s_waitcnt vmcnt(18)
	v_lshlrev_b32_e32 v56, 16, v20
	v_and_b32_e32 v57, 0xffff0000, v20
	s_waitcnt vmcnt(16)
	v_lshlrev_b32_e32 v60, 16, v16
	v_and_b32_e32 v61, 0xffff0000, v16
	v_lshlrev_b32_e32 v16, 16, v17
	v_and_b32_e32 v17, 0xffff0000, v17
	s_waitcnt vmcnt(14)
	v_lshlrev_b32_e32 v64, 16, v28
	v_and_b32_e32 v65, 0xffff0000, v28
	v_lshlrev_b32_e32 v28, 16, v29
	v_and_b32_e32 v29, 0xffff0000, v29
	s_waitcnt vmcnt(13)
	v_lshlrev_b32_e32 v66, 16, v30
	v_and_b32_e32 v67, 0xffff0000, v30
	s_waitcnt vmcnt(11)
	v_lshlrev_b32_e32 v70, 16, v34
	v_and_b32_e32 v71, 0xffff0000, v34
	v_lshlrev_b32_e32 v34, 16, v35
	v_and_b32_e32 v35, 0xffff0000, v35
	v_lshlrev_b32_e32 v20, 16, v21
	v_and_b32_e32 v21, 0xffff0000, v21
	v_lshlrev_b32_e32 v58, 16, v22
	v_and_b32_e32 v59, 0xffff0000, v22
	v_lshlrev_b32_e32 v30, 16, v31
	v_and_b32_e32 v31, 0xffff0000, v31
	v_lshlrev_b32_e32 v68, 16, v32
	v_and_b32_e32 v69, 0xffff0000, v32
	v_pk_add_f32 v[18:19], v[28:29], v[18:19]
	v_pk_add_f32 v[28:29], v[66:67], v[56:57]
	v_pk_add_f32 v[16:17], v[34:35], v[16:17]
	s_waitcnt vmcnt(10)
	v_lshlrev_b32_e32 v34, 16, v36
	v_and_b32_e32 v35, 0xffff0000, v36
	v_lshlrev_b32_e32 v22, 16, v23
	v_and_b32_e32 v23, 0xffff0000, v23
	v_lshlrev_b32_e32 v32, 16, v33
	v_and_b32_e32 v33, 0xffff0000, v33
	v_pk_add_f32 v[20:21], v[30:31], v[20:21]
	v_pk_add_f32 v[30:31], v[68:69], v[58:59]
	v_pk_add_f32 v[28:29], v[28:29], v[34:35]
	s_waitcnt vmcnt(9)
	v_lshlrev_b32_e32 v34, 16, v38
	v_and_b32_e32 v35, 0xffff0000, v38
	v_lshlrev_b32_e32 v62, 16, v26
	v_and_b32_e32 v63, 0xffff0000, v26
	v_lshlrev_b32_e32 v26, 16, v27
	v_pk_add_f32 v[54:55], v[64:65], v[54:55]
	v_pk_add_f32 v[22:23], v[32:33], v[22:23]
	v_pk_add_f32 v[32:33], v[70:71], v[60:61]
	v_and_b32_e32 v27, 0xffff0000, v27
	v_pk_add_f32 v[30:31], v[30:31], v[34:35]
	s_waitcnt vmcnt(8)
	v_lshlrev_b32_e32 v34, 16, v24
	v_and_b32_e32 v35, 0xffff0000, v24
	v_lshlrev_b32_e32 v24, 16, v25
	v_and_b32_e32 v25, 0xffff0000, v25
	v_pk_add_f32 v[18:19], v[18:19], v[26:27]
	v_pk_add_f32 v[26:27], v[54:55], v[62:63]
	v_pk_add_f32 v[16:17], v[16:17], v[24:25]
	v_pk_add_f32 v[24:25], v[32:33], v[34:35]
	v_lshlrev_b32_e32 v36, 16, v37
	v_and_b32_e32 v37, 0xffff0000, v37
	v_pk_add_f32 v[20:21], v[20:21], v[36:37]
	v_lshlrev_b32_e32 v36, 16, v39
	v_and_b32_e32 v37, 0xffff0000, v39
	v_pk_add_f32 v[22:23], v[22:23], v[36:37]
	s_waitcnt vmcnt(7)
	v_lshlrev_b32_e32 v32, 16, v42
	v_and_b32_e32 v33, 0xffff0000, v42
	v_pk_add_f32 v[26:27], v[26:27], v[32:33]
	s_waitcnt vmcnt(6)
; __device__ __forceinline__ unsigned pk2(float lo, float hi) { return pg8::cvt_pk_bf16(lo, hi); }
; template <bool FINAL>
; __device__ __forceinline__ void sample_fixup(const Params& p, int S, float* ss_s, const float* gf) {
;     ...
;             for (int j = 0; j < 4; ++j) { const unsigned long long w = pr[64 * j]; const unsigned lo = (unsigned)w, hi = (unsigned)(w >> 32);
;                 v[j] += (f32x4){__uint_as_float(lo << 16), __uint_as_float(lo & 0xffff0000u), __uint_as_float(hi << 16), __uint_as_float(hi & 0xffff0000u)}; }
;         }
;         float s = 0.f;
; #pragma unroll
;         for (int j = 0; j < 4; ++j) s += (v[j][0] * v[j][0] + v[j][1] * v[j][1]) + (v[j][2] * v[j][2] + v[j][3] * v[j][3]);
;         s = wave_sum(s);
;         if (!FINAL) {
; #pragma unroll
;             for (int j = 0; j < 4; ++j) o8[64 * j] = (unsigned long long)pk2(v[j][0], v[j][1]) | ((unsigned long long)pk2(v[j][2], v[j][3]) << 32);
;             if (lane == 0) ss_s[r] = s;
; template <int layer>
; __device__ __forceinline__ void run_layer(const Params& p, LAS unsigned char* lds, const XcdBarrier& xbar, const int lo, const int hi) {
;     ...
;                 asm volatile("s_waitcnt vmcnt(0)" ::: "memory");
;                 __syncthreads();
;                 if (threadIdx.x == 0) {
;                     __builtin_amdgcn_fence(__ATOMIC_RELEASE, "agent");
;                     asm volatile("s_waitcnt vmcnt(0)" ::: "memory");
;                     __hip_atomic_fetch_add((unsigned*)(ws + WS_BAR + 16384 + 4096 * layer), 1u, __ATOMIC_RELAXED, __HIP_MEMORY_SCOPE_AGENT);
;                 }
	v_lshlrev_b32_e32 v32, 16, v44
	v_and_b32_e32 v33, 0xffff0000, v44
	v_lshlrev_b32_e32 v34, 16, v43
	v_and_b32_e32 v35, 0xffff0000, v43
	v_pk_add_f32 v[28:29], v[28:29], v[32:33]
	s_waitcnt vmcnt(5)
	v_lshlrev_b32_e32 v32, 16, v46
	v_and_b32_e32 v33, 0xffff0000, v46
	v_pk_add_f32 v[18:19], v[18:19], v[34:35]
	v_lshlrev_b32_e32 v34, 16, v45
	v_and_b32_e32 v35, 0xffff0000, v45
	v_pk_add_f32 v[30:31], v[30:31], v[32:33]
	s_waitcnt vmcnt(4)
	v_lshlrev_b32_e32 v32, 16, v40
	v_and_b32_e32 v33, 0xffff0000, v40
	v_pk_add_f32 v[20:21], v[20:21], v[34:35]
	v_lshlrev_b32_e32 v34, 16, v47
	v_and_b32_e32 v35, 0xffff0000, v47
	v_pk_add_f32 v[24:25], v[24:25], v[32:33]
	s_waitcnt vmcnt(3)
	v_lshlrev_b32_e32 v32, 16, v48
	v_and_b32_e32 v33, 0xffff0000, v48
	v_pk_add_f32 v[22:23], v[22:23], v[34:35]
	v_lshlrev_b32_e32 v34, 16, v41
	v_and_b32_e32 v35, 0xffff0000, v41
	v_pk_add_f32 v[26:27], v[26:27], v[32:33]
	s_waitcnt vmcnt(2)
	v_lshlrev_b32_e32 v32, 16, v50
	v_and_b32_e32 v33, 0xffff0000, v50
	v_pk_add_f32 v[16:17], v[16:17], v[34:35]
	v_lshlrev_b32_e32 v34, 16, v49
	v_and_b32_e32 v35, 0xffff0000, v49
	v_pk_add_f32 v[28:29], v[28:29], v[32:33]
	s_waitcnt vmcnt(1)
	v_lshlrev_b32_e32 v32, 16, v52
	v_and_b32_e32 v33, 0xffff0000, v52
	v_pk_add_f32 v[18:19], v[18:19], v[34:35]
	v_pk_add_f32 v[30:31], v[30:31], v[32:33]
	s_waitcnt vmcnt(0)
	v_lshlrev_b32_e32 v32, 16, v14
	v_and_b32_e32 v33, 0xffff0000, v14
	v_lshlrev_b32_e32 v14, 16, v15
	v_and_b32_e32 v15, 0xffff0000, v15
	v_lshlrev_b32_e32 v34, 16, v51
	v_and_b32_e32 v35, 0xffff0000, v51
	v_pk_add_f32 v[16:17], v[16:17], v[14:15]
	v_mul_f32_e32 v1, v27, v27
	v_mul_f32_e32 v14, v19, v19
	v_pk_add_f32 v[20:21], v[20:21], v[34:35]
	v_fmac_f32_e32 v1, v26, v26
	v_fmac_f32_e32 v14, v18, v18
	v_add_f32_e32 v1, v1, v14
	v_mul_f32_e32 v14, v29, v29
	v_mul_f32_e32 v15, v21, v21
	v_lshlrev_b32_e32 v34, 16, v53
	v_and_b32_e32 v35, 0xffff0000, v53
	v_fmac_f32_e32 v14, v28, v28
	v_fmac_f32_e32 v15, v20, v20
	v_pk_add_f32 v[22:23], v[22:23], v[34:35]
	v_add_f32_e32 v14, v14, v15
	v_add_f32_e32 v1, v1, v14
	v_mul_f32_e32 v14, v31, v31
	v_mul_f32_e32 v15, v23, v23
	v_fmac_f32_e32 v14, v30, v30
	v_fmac_f32_e32 v15, v22, v22
	v_pk_add_f32 v[24:25], v[24:25], v[32:33]
	v_add_f32_e32 v14, v14, v15
	v_add_f32_e32 v1, v1, v14
	v_mul_f32_e32 v14, v25, v25
	v_mul_f32_e32 v15, v17, v17
	v_fmac_f32_e32 v14, v24, v24
	v_fmac_f32_e32 v15, v16, v16
	v_add_f32_e32 v14, v14, v15
	v_add_f32_e32 v1, v1, v14
	ds_bpermute_b32 v14, v8, v1
	v_cvt_pk_bf16_f32 v26, v26, v27
	v_cvt_pk_bf16_f32 v27, v18, v19
	global_store_dwordx2 v[6:7], v[26:27], off sc1
	v_cvt_pk_bf16_f32 v18, v28, v29
	s_waitcnt lgkmcnt(0)
	v_add_f32_e32 v1, v1, v14
	ds_bpermute_b32 v14, v9, v1
	v_cvt_pk_bf16_f32 v19, v20, v21
	global_store_dwordx2 v[6:7], v[18:19], off offset:512 sc1
	v_cvt_pk_bf16_f32 v18, v30, v31
	v_cvt_pk_bf16_f32 v19, v22, v23
	s_waitcnt lgkmcnt(0)
	v_add_f32_e32 v1, v1, v14
	ds_bpermute_b32 v14, v10, v1
	global_store_dwordx2 v[6:7], v[18:19], off offset:1024 sc1
	v_cvt_pk_bf16_f32 v18, v24, v25
	v_cvt_pk_bf16_f32 v19, v16, v17
	global_store_dwordx2 v[6:7], v[18:19], off offset:1536 sc1
	s_waitcnt lgkmcnt(0)
	v_add_f32_e32 v1, v1, v14
	ds_bpermute_b32 v14, v11, v1
	s_waitcnt lgkmcnt(0)
	v_add_f32_e32 v1, v1, v14
	ds_bpermute_b32 v14, v12, v1
	s_waitcnt lgkmcnt(0)
	v_add_f32_e32 v1, v1, v14
	ds_bpermute_b32 v14, v13, v1
	s_and_saveexec_b64 s[2:3], s[0:1]
	s_cbranch_execz .LBB0_467
	s_waitcnt lgkmcnt(0)
	v_add_f32_e32 v1, v1, v14
	v_lshl_add_u64 v[6:7], s[72:73], 0, v[2:3]
	global_store_dword v[6:7], v1, off sc1
	s_branch .LBB0_467
.LBB0_470:
	s_or_b64 exec, exec, s[4:5]
	s_waitcnt vmcnt(0)
	s_waitcnt lgkmcnt(0)
	s_barrier
	s_mov_b64 s[0:1], exec
	v_readlane_b32 s2, v254, 3
	v_readlane_b32 s3, v254, 4
	s_and_b64 s[2:3], s[0:1], s[2:3]
	s_mov_b64 exec, s[2:3]
	s_cbranch_execz .LBB0_473
	s_mov_b64 s[2:3], exec
	v_mbcnt_lo_u32_b32 v0, s2, 0
	s_nop 0
	s_waitcnt vmcnt(0)
	s_waitcnt vmcnt(0)
	v_mbcnt_hi_u32_b32 v0, s3, v0
	v_cmp_eq_u32_e32 vcc, 0, v0
	s_and_b64 s[4:5], exec, vcc
	s_mov_b64 exec, s[4:5]
	s_cbranch_execz .LBB0_473
	s_bcnt1_i32_b64 s2, s[2:3]
	v_mov_b32_e32 v0, 0x84000
	v_mov_b32_e32 v1, s2
	global_atomic_add v0, v1, s[72:73]

; template <bool FINAL>
; __device__ __forceinline__ void sample_fixup(const Params& p, int S, float* ss_s, const float* gf) {
;     ...
;         for (int j = 0; j < 4; ++j) { const unsigned long long w = o8[64 * j]; const unsigned lo = (unsigned)w, hi = (unsigned)(w >> 32);
;             v[j] = (f32x4){__uint_as_float(lo << 16), __uint_as_float(lo & 0xffff0000u), __uint_as_float(hi << 16), __uint_as_float(hi & 0xffff0000u)}; }
;         for (int sp = 0; sp < S; ++sp) {
;             const unsigned long long* pr = (const unsigned long long*)((const bf16*)part + ((size_t)sp * MS + r) * D) + lane;
; #pragma unroll
;             for (int j = 0; j < 4; ++j) { const unsigned long long w = pr[64 * j]; const unsigned lo = (unsigned)w, hi = (unsigned)(w >> 32);
;                 v[j] += (f32x4){__uint_as_float(lo << 16), __uint_as_float(lo & 0xffff0000u), __uint_as_float(hi << 16), __uint_as_float(hi & 0xffff0000u)}; }
;         }
.LBB0_1165:
	s_waitcnt lgkmcnt(0)
	v_lshl_add_u64 v[14:15], s[72:73], 0, v[4:5]
	v_add_co_u32_e32 v16, vcc, s6, v14
	v_add_co_u32_e64 v24, s[2:3], s7, v14
	s_nop 0
	v_addc_co_u32_e32 v17, vcc, 0, v15, vcc
	v_addc_co_u32_e64 v25, s[2:3], 0, v15, s[2:3]
	global_load_dwordx2 v[18:19], v[16:17], off
	global_load_dwordx2 v[20:21], v[16:17], off offset:512
	global_load_dwordx2 v[22:23], v[16:17], off offset:1024
	global_load_dwordx2 v[26:27], v[24:25], off
	v_add_co_u32_e32 v6, vcc, 0x4e00000, v14
	global_load_dwordx2 v[16:17], v[16:17], off offset:1536
	s_nop 0
	v_addc_co_u32_e32 v7, vcc, 0, v15, vcc
	global_load_dwordx2 v[28:29], v[6:7], off
	global_load_dwordx2 v[30:31], v[6:7], off offset:512
	global_load_dwordx2 v[32:33], v[6:7], off offset:1024
	global_load_dwordx2 v[34:35], v[6:7], off offset:1536
	global_load_dwordx2 v[36:37], v[24:25], off offset:512
	global_load_dwordx2 v[38:39], v[24:25], off offset:1024
	global_load_dwordx2 v[40:41], v[24:25], off offset:1536
	v_add_co_u32_e32 v24, vcc, s8, v14
	s_waitcnt vmcnt(9)
	v_lshlrev_b32_e32 v58, 16, v22
	v_addc_co_u32_e32 v25, vcc, 0, v15, vcc
	global_load_dwordx2 v[42:43], v[24:25], off
	global_load_dwordx2 v[44:45], v[24:25], off offset:512
	v_add_co_u32_e32 v14, vcc, s9, v14
	s_waitcnt vmcnt(8)
	v_lshlrev_b32_e32 v64, 16, v28
	v_addc_co_u32_e32 v15, vcc, 0, v15, vcc
	global_load_dwordx2 v[46:47], v[24:25], off offset:1024
	global_load_dwordx2 v[48:49], v[24:25], off offset:1536
	global_load_dwordx2 v[50:51], v[14:15], off
	global_load_dwordx2 v[52:53], v[14:15], off offset:512
	global_load_dwordx2 v[54:55], v[14:15], off offset:1024
	global_load_dwordx2 v[56:57], v[14:15], off offset:1536
	v_lshlrev_b32_e32 v14, 16, v18
	v_and_b32_e32 v15, 0xffff0000, v18
	v_lshlrev_b32_e32 v18, 16, v19
	v_and_b32_e32 v19, 0xffff0000, v19
	v_and_b32_e32 v65, 0xffff0000, v28
	v_lshlrev_b32_e32 v28, 16, v29
	v_and_b32_e32 v29, 0xffff0000, v29
	v_lshlrev_b32_e32 v24, 16, v20
	v_and_b32_e32 v25, 0xffff0000, v20
	v_lshlrev_b32_e32 v62, 16, v26
	v_and_b32_e32 v63, 0xffff0000, v26
	v_lshlrev_b32_e32 v26, 16, v27
	s_waitcnt vmcnt(13)
	v_lshlrev_b32_e32 v66, 16, v30
	v_and_b32_e32 v67, 0xffff0000, v30
	v_pk_add_f32 v[18:19], v[28:29], v[18:19]
	v_and_b32_e32 v27, 0xffff0000, v27
	v_and_b32_e32 v59, 0xffff0000, v22
	s_waitcnt vmcnt(12)
	v_lshlrev_b32_e32 v68, 16, v32
	v_and_b32_e32 v69, 0xffff0000, v32
	v_pk_add_f32 v[24:25], v[66:67], v[24:25]
	v_pk_add_f32 v[18:19], v[18:19], v[26:27]
	s_waitcnt vmcnt(10)
	v_lshlrev_b32_e32 v26, 16, v36
	v_and_b32_e32 v27, 0xffff0000, v36
	v_lshlrev_b32_e32 v20, 16, v21
	v_and_b32_e32 v21, 0xffff0000, v21
	v_lshlrev_b32_e32 v22, 16, v23
	v_and_b32_e32 v23, 0xffff0000, v23
	v_lshlrev_b32_e32 v60, 16, v16
	v_and_b32_e32 v61, 0xffff0000, v16
	v_lshlrev_b32_e32 v30, 16, v31
	v_and_b32_e32 v31, 0xffff0000, v31
	v_lshlrev_b32_e32 v32, 16, v33
	v_and_b32_e32 v33, 0xffff0000, v33
	v_lshlrev_b32_e32 v70, 16, v34
	v_and_b32_e32 v71, 0xffff0000, v34
	v_pk_add_f32 v[28:29], v[68:69], v[58:59]
	v_pk_add_f32 v[24:25], v[24:25], v[26:27]
	s_waitcnt vmcnt(9)
	v_lshlrev_b32_e32 v26, 16, v38
	v_and_b32_e32 v27, 0xffff0000, v38
	v_pk_add_f32 v[14:15], v[64:65], v[14:15]
	v_pk_add_f32 v[20:21], v[30:31], v[20:21]
	v_pk_add_f32 v[22:23], v[32:33], v[22:23]
	v_pk_add_f32 v[30:31], v[70:71], v[60:61]
	v_lshlrev_b32_e32 v32, 16, v37
	v_and_b32_e32 v33, 0xffff0000, v37
	v_pk_add_f32 v[26:27], v[28:29], v[26:27]
	s_waitcnt vmcnt(8)
	v_lshlrev_b32_e32 v28, 16, v40
	v_and_b32_e32 v29, 0xffff0000, v40
	v_lshlrev_b32_e32 v16, 16, v17
	v_and_b32_e32 v17, 0xffff0000, v17
	v_lshlrev_b32_e32 v34, 16, v35
	v_and_b32_e32 v35, 0xffff0000, v35
	v_pk_add_f32 v[14:15], v[14:15], v[62:63]
	v_pk_add_f32 v[20:21], v[20:21], v[32:33]
	v_lshlrev_b32_e32 v32, 16, v39
	v_and_b32_e32 v33, 0xffff0000, v39
	v_pk_add_f32 v[28:29], v[30:31], v[28:29]
	v_pk_add_f32 v[16:17], v[34:35], v[16:17]
	v_pk_add_f32 v[22:23], v[22:23], v[32:33]
	v_lshlrev_b32_e32 v32, 16, v41
	v_and_b32_e32 v33, 0xffff0000, v41
	v_pk_add_f32 v[16:17], v[16:17], v[32:33]
	s_waitcnt vmcnt(7)
	v_lshlrev_b32_e32 v30, 16, v42
	v_and_b32_e32 v31, 0xffff0000, v42
	v_pk_add_f32 v[14:15], v[14:15], v[30:31]
	s_waitcnt vmcnt(6)
; __device__ __forceinline__ unsigned pk2(float lo, float hi) { return pg8::cvt_pk_bf16(lo, hi); }
; template <bool FINAL>
; __device__ __forceinline__ void sample_fixup(const Params& p, int S, float* ss_s, const float* gf) {
;     ...
;             for (int j = 0; j < 4; ++j) { const unsigned long long w = pr[64 * j]; const unsigned lo = (unsigned)w, hi = (unsigned)(w >> 32);
;                 v[j] += (f32x4){__uint_as_float(lo << 16), __uint_as_float(lo & 0xffff0000u), __uint_as_float(hi << 16), __uint_as_float(hi & 0xffff0000u)}; }
;         }
;         float s = 0.f;
; #pragma unroll
;         for (int j = 0; j < 4; ++j) s += (v[j][0] * v[j][0] + v[j][1] * v[j][1]) + (v[j][2] * v[j][2] + v[j][3] * v[j][3]);
;         s = wave_sum(s);
;         if (!FINAL) {
; #pragma unroll
;             for (int j = 0; j < 4; ++j) o8[64 * j] = (unsigned long long)pk2(v[j][0], v[j][1]) | ((unsigned long long)pk2(v[j][2], v[j][3]) << 32);
;             if (lane == 0) ss_s[r] = s;
; template <int layer>
; __device__ __forceinline__ void run_layer(const Params& p, LAS unsigned char* lds, const XcdBarrier& xbar, const int lo, const int hi) {
;     ...
;                 asm volatile("s_waitcnt vmcnt(0)" ::: "memory");
;                 __syncthreads();
;                 if (threadIdx.x == 0) {
;                     __builtin_amdgcn_fence(__ATOMIC_RELEASE, "agent");
;                     asm volatile("s_waitcnt vmcnt(0)" ::: "memory");
;                     __hip_atomic_fetch_add((unsigned*)(ws + WS_BAR + 16384 + 4096 * layer), 1u, __ATOMIC_RELAXED, __HIP_MEMORY_SCOPE_AGENT);
;                 }
	v_lshlrev_b32_e32 v30, 16, v44
	v_and_b32_e32 v31, 0xffff0000, v44
	v_lshlrev_b32_e32 v32, 16, v43
	v_and_b32_e32 v33, 0xffff0000, v43
	v_pk_add_f32 v[24:25], v[24:25], v[30:31]
	s_waitcnt vmcnt(5)
	v_lshlrev_b32_e32 v30, 16, v46
	v_and_b32_e32 v31, 0xffff0000, v46
	v_pk_add_f32 v[18:19], v[18:19], v[32:33]
	v_lshlrev_b32_e32 v32, 16, v45
	v_and_b32_e32 v33, 0xffff0000, v45
	v_pk_add_f32 v[26:27], v[26:27], v[30:31]
	s_waitcnt vmcnt(4)
	v_lshlrev_b32_e32 v30, 16, v48
	v_and_b32_e32 v31, 0xffff0000, v48
	v_pk_add_f32 v[20:21], v[20:21], v[32:33]
	v_lshlrev_b32_e32 v32, 16, v47
	v_and_b32_e32 v33, 0xffff0000, v47
	v_pk_add_f32 v[28:29], v[28:29], v[30:31]
	s_waitcnt vmcnt(3)
	v_lshlrev_b32_e32 v30, 16, v50
	v_and_b32_e32 v31, 0xffff0000, v50
	v_pk_add_f32 v[22:23], v[22:23], v[32:33]
	v_lshlrev_b32_e32 v32, 16, v49
	v_and_b32_e32 v33, 0xffff0000, v49
	v_pk_add_f32 v[30:31], v[14:15], v[30:31]
	s_waitcnt vmcnt(2)
	v_lshlrev_b32_e32 v14, 16, v52
	v_and_b32_e32 v15, 0xffff0000, v52
	v_pk_add_f32 v[16:17], v[16:17], v[32:33]
	v_lshlrev_b32_e32 v32, 16, v51
	v_and_b32_e32 v33, 0xffff0000, v51
	v_pk_add_f32 v[24:25], v[24:25], v[14:15]
	s_waitcnt vmcnt(1)
	v_lshlrev_b32_e32 v14, 16, v54
	v_and_b32_e32 v15, 0xffff0000, v54
	v_pk_add_f32 v[18:19], v[18:19], v[32:33]
	v_pk_add_f32 v[26:27], v[26:27], v[14:15]
	s_waitcnt vmcnt(0)
	v_lshlrev_b32_e32 v14, 16, v56
	v_and_b32_e32 v15, 0xffff0000, v56
	v_lshlrev_b32_e32 v32, 16, v53
	v_and_b32_e32 v33, 0xffff0000, v53
	v_pk_add_f32 v[28:29], v[28:29], v[14:15]
	v_mul_f32_e32 v1, v31, v31
	v_mul_f32_e32 v14, v19, v19
	v_pk_add_f32 v[20:21], v[20:21], v[32:33]
	v_fmac_f32_e32 v1, v30, v30
	v_fmac_f32_e32 v14, v18, v18
	v_add_f32_e32 v1, v1, v14
	v_mul_f32_e32 v14, v25, v25
	v_mul_f32_e32 v15, v21, v21
	v_lshlrev_b32_e32 v32, 16, v55
	v_and_b32_e32 v33, 0xffff0000, v55
	v_fmac_f32_e32 v14, v24, v24
	v_fmac_f32_e32 v15, v20, v20
	v_pk_add_f32 v[22:23], v[22:23], v[32:33]
	v_add_f32_e32 v14, v14, v15
	v_add_f32_e32 v1, v1, v14
	v_mul_f32_e32 v14, v27, v27
	v_mul_f32_e32 v15, v23, v23
	v_lshlrev_b32_e32 v32, 16, v57
	v_and_b32_e32 v33, 0xffff0000, v57
	v_fmac_f32_e32 v14, v26, v26
	v_fmac_f32_e32 v15, v22, v22
	v_pk_add_f32 v[16:17], v[16:17], v[32:33]
	v_add_f32_e32 v14, v14, v15
	v_add_f32_e32 v1, v1, v14
	v_mul_f32_e32 v14, v29, v29
	v_mul_f32_e32 v15, v17, v17
	v_fmac_f32_e32 v14, v28, v28
	v_fmac_f32_e32 v15, v16, v16
	v_add_f32_e32 v14, v14, v15
	v_add_f32_e32 v1, v1, v14
	ds_bpermute_b32 v14, v8, v1
	v_cvt_pk_bf16_f32 v30, v30, v31
	v_cvt_pk_bf16_f32 v31, v18, v19
	global_store_dwordx2 v[6:7], v[30:31], off sc1
	v_cvt_pk_bf16_f32 v18, v24, v25
	s_waitcnt lgkmcnt(0)
	v_add_f32_e32 v1, v1, v14
	ds_bpermute_b32 v14, v9, v1
	v_cvt_pk_bf16_f32 v19, v20, v21
	global_store_dwordx2 v[6:7], v[18:19], off offset:512 sc1
	v_cvt_pk_bf16_f32 v18, v26, v27
	v_cvt_pk_bf16_f32 v19, v22, v23
	s_waitcnt lgkmcnt(0)
	v_add_f32_e32 v1, v1, v14
	ds_bpermute_b32 v14, v10, v1
	global_store_dwordx2 v[6:7], v[18:19], off offset:1024 sc1
	v_cvt_pk_bf16_f32 v18, v28, v29
	v_cvt_pk_bf16_f32 v19, v16, v17
	global_store_dwordx2 v[6:7], v[18:19], off offset:1536 sc1
	s_waitcnt lgkmcnt(0)
	v_add_f32_e32 v1, v1, v14
	ds_bpermute_b32 v14, v11, v1
	s_waitcnt lgkmcnt(0)
	v_add_f32_e32 v1, v1, v14
	ds_bpermute_b32 v14, v12, v1
	s_waitcnt lgkmcnt(0)
	v_add_f32_e32 v1, v1, v14
	ds_bpermute_b32 v14, v13, v1
	s_and_saveexec_b64 s[2:3], s[0:1]
	s_cbranch_execz .LBB0_1164
	s_waitcnt lgkmcnt(0)
	v_add_f32_e32 v1, v1, v14
	v_lshl_add_u64 v[6:7], s[72:73], 0, v[2:3]
	global_store_dword v[6:7], v1, off sc1
	s_branch .LBB0_1164
.LBB0_1167:
	s_or_b64 exec, exec, s[16:17]
	s_waitcnt vmcnt(0)
	s_waitcnt lgkmcnt(0)
	s_barrier
	s_mov_b64 s[0:1], exec
	v_readlane_b32 s2, v254, 3
	v_readlane_b32 s3, v254, 4
	s_and_b64 s[2:3], s[0:1], s[2:3]
	s_mov_b64 exec, s[2:3]
	s_cbranch_execz .LBB0_1170
	s_mov_b64 s[2:3], exec
	v_mbcnt_lo_u32_b32 v0, s2, 0
	s_nop 0
	s_waitcnt vmcnt(0)
	s_waitcnt vmcnt(0)
	v_mbcnt_hi_u32_b32 v0, s3, v0
	v_cmp_eq_u32_e32 vcc, 0, v0
	s_and_b64 s[6:7], exec, vcc
	s_mov_b64 exec, s[6:7]
	s_cbranch_execz .LBB0_1170
	s_bcnt1_i32_b64 s2, s[2:3]
	v_mov_b32_e32 v0, 0x85000
	v_mov_b32_e32 v1, s2
	global_atomic_add v0, v1, s[72:73]
